# attention inner loop rewritten: only the 17 key tiles that can intersect the window are processed per query tile, deep-pipelined LDS reads
# speedup vs baseline: 1.0899x; 1.0035x over previous
; #define LAS __attribute__((address_space(3)))
; __device__ void attn_mfma(const Params& p, int l, const bf16_t* proj, bf16_t* y0, LAS unsigned char* lds) {
;     ...
;     const int tid = fresh_tid(), lane = tid & 63, wv = tid >> 6, fr = lane & 15, g = lane >> 4;
;     for (int it = blockIdx.x; it < 256; it += gridDim.x) {
;         const int n = it >> 1, hk = it & 1, kbase = (n - 1) * 128;
;         __syncthreads();
;         {
;             u32x4 kreg[6], va[3], vb[3];
; #pragma unroll
;             for (int q = 0; q < 6; ++q) { const int c = tid + q * NTHREADS, row = c >> 3, part = c & 7, s = kbase + row;
;                 kreg[q] = (u32x4){0u, 0u, 0u, 0u}; if (s >= 0 && s < SEQ) kreg[q] = *(const u32x4*)(proj + (size_t)s * NP + AK + hk * 64 + part * 8); }
; #pragma unroll
;             for (int q = 0; q < 3; ++q) { const int c = tid + q * NTHREADS, pr = c >> 3, part = c & 7, s = kbase + pr * 2;
;                 va[q] = (u32x4){0u, 0u, 0u, 0u}; vb[q] = (u32x4){0u, 0u, 0u, 0u};
;                 if (s >= 0 && s < SEQ) { va[q] = *(const u32x4*)(proj + (size_t)s * NP + AV + hk * 64 + part * 8); vb[q] = *(const u32x4*)(proj + (size_t)(s + 1) * NP + AV + hk * 64 + part * 8); } }
; #pragma unroll
;             for (int q = 0; q < 6; ++q) { const int c = tid + q * NTHREADS, row = c >> 3, part = c & 7; *(LAS u32x4*)(Ks + row * KP + part * 8) = kreg[q]; }
; #pragma unroll
;             for (int q = 0; q < 3; ++q) { const int c = tid + q * NTHREADS, pr = c >> 3, part = c & 7; const u32x4 a = va[q], b = vb[q];
; #pragma unroll
;                 for (int e = 0; e < 4; ++e) {
;                     *(LAS unsigned*)(Vt + (part * 8 + 2 * e) * VP + pr * 2) = (a[e] & 0xffffu) | (b[e] << 16);
;                     *(LAS unsigned*)(Vt + (part * 8 + 2 * e + 1) * VP + pr * 2) = (a[e] >> 16) | (b[e] & 0xffff0000u); } }
;         }
;         const int hq = hk * 4 + (wv >> 1);
;         bf16x8 qn[2];
; #pragma unroll
;         for (int ks = 0; ks < 2; ++ks) qn[ks] = *(const bf16x8*)(proj + (size_t)(n * 128 + (wv & 1) * 64 + fr) * NP + AQ + hq * 64 + ks * 32 + g * 8);
;         __syncthreads();
;         const float slope = exp2f(-(float)(hq + 1)), sink = p.attn_sink[l * 8 + hq];
;         const bool edge = (n == 0) || (n == SEQ / 128 - 1);
;         for (int tile = 0; tile < 4; ++tile) {
;             const int tl = (wv & 1) * 64 + tile * 16 + fr, t = n * 128 + tl;
.LBB0_455:
	s_andn2_b64 vcc, exec, s[4:5]
	s_cbranch_vccnz .LBB0_511
	v_readlane_b32 s4, v255, 38
	s_cmp_gt_i32 s4, 0
	s_mov_b64 s[4:5], -1
	s_cbranch_scc0 .LBB0_493
	v_readlane_b32 s4, v252, 61
	v_readlane_b32 s5, v252, 62
	v_readlane_b32 s20, v253, 11
	s_waitcnt vmcnt(0)
	v_mov_b32_e32 v0, v213
	s_andn2_b64 vcc, exec, s[4:5]
	v_readlane_b32 s18, v253, 10
	v_readlane_b32 s21, v253, 12
	v_readlane_b32 s19, v254, 35
	s_movk_i32 s66, 0x1000
	s_movk_i32 s22, 0x4000
	s_movk_i32 s23, 0x1c00
	s_mov_b64 s[24:25], 0x1800
	s_cbranch_vccnz .LBB0_480
	v_and_b32_e32 v6, 64, v211
	v_xor_b32_e32 v5, 16, v211
	v_add_u32_e32 v6, 64, v6
	v_cmp_lt_i32_e32 vcc, v5, v6
	v_bfe_u32 v2, v0, 4, 2
	v_readlane_b32 s4, v254, 7
	v_cndmask_b32_e32 v5, v211, v5, vcc
	v_add_u32_e32 v8, 0x600, v0
	v_lshlrev_b32_e32 v110, 3, v2
	v_mov_b32_e32 v111, v189
	v_lshlrev_b32_e32 v121, 2, v5
	v_xor_b32_e32 v5, 32, v211
	v_readlane_b32 s5, v254, 8
	v_ashrrev_i32_e32 v125, 3, v8
	v_add_u32_e32 v8, 0x800, v0
	v_and_b32_e32 v1, 15, v0
	v_lshlrev_b32_e32 v3, 3, v0
	v_ashrrev_i32_e32 v109, 7, v0
	v_and_b32_e32 v120, 0x4f, v0
	v_cmp_lt_i32_e32 vcc, v5, v6
	v_lshl_add_u64 v[112:113], s[4:5], 0, v[110:111]
	v_ashrrev_i32_e32 v111, 3, v0
	v_add_u32_e32 v6, 0x200, v0
	v_add_u32_e32 v7, 0x400, v0
	v_ashrrev_i32_e32 v126, 3, v8
	v_add_u32_e32 v8, 0xa00, v0
	v_ashrrev_i32_e32 v0, 2, v0
	v_and_b32_e32 v128, -2, v0
	v_ashrrev_i32_e32 v0, 2, v6
	v_and_b32_e32 v108, 56, v3
	v_ashrrev_i32_e32 v123, 3, v6
	v_ashrrev_i32_e32 v124, 3, v7
	v_ashrrev_i32_e32 v127, 3, v8
	v_and_b32_e32 v129, -2, v0
	v_ashrrev_i32_e32 v0, 2, v7
	s_movk_i32 s4, 0x90
	v_lshl_add_u32 v3, v108, 1, 0
	v_and_b32_e32 v130, -2, v0
	v_mul_lo_u32 v0, v111, s4
	v_mul_lo_u32 v6, v123, s4
	v_mul_lo_u32 v7, v124, s4
	v_mul_lo_u32 v8, v125, s4
	v_mul_lo_u32 v9, v126, s4
	v_mul_lo_u32 v10, v127, s4
	s_movk_i32 s4, 0x30e
	v_lshl_add_u32 v4, v2, 4, 0
	v_lshlrev_b32_e32 v2, 2, v2
	v_cndmask_b32_e32 v5, v211, v5, vcc
	v_mad_u32_u24 v11, v108, s4, v3
	s_movk_i32 s4, 0x310
	v_mov_b32_e32 v13, 0x3100
	v_mov_b32_e32 v14, 0x6200
	v_mov_b32_e32 v15, 0x9300
	v_lshlrev_b32_e32 v122, 2, v5
	v_sub_u32_e32 v5, v4, v110
	v_lshl_add_u32 v131, v128, 1, v11
	v_lshl_add_u32 v132, v129, 1, v11
	v_lshl_add_u32 v133, v130, 1, v11
	v_mul_u32_u24_e32 v11, 0x90, v1
	v_mul_u32_u24_e32 v12, 0x310, v1
	v_mad_u32_u24 v13, v1, s4, v13
	v_mad_u32_u24 v14, v1, s4, v14
	v_mad_u32_u24 v1, v1, s4, v15
	v_sub_u32_e32 v2, v120, v2
	s_lshl_b32 s10, s26, 3
	v_add_u32_e32 v134, 0x80, v2
	v_add_u32_e32 v135, v3, v0
	v_add_u32_e32 v136, v3, v6
	v_add_u32_e32 v137, v3, v7
	v_add_u32_e32 v138, v3, v8
	v_add_u32_e32 v139, v3, v9
	v_add_u32_e32 v140, v3, v10
	v_add_u32_e32 v141, v4, v11
	v_add_u32_e32 v142, v5, v12
	v_add_u32_e32 v143, v5, v13
	v_add_u32_e32 v144, v5, v14
	v_add_u32_e32 v145, v5, v1
	v_and_b32_e32 v185, 64, v120
	v_mul_u32_u24_e32 v186, 0x90, v185
	v_add_u32_e32 v174, v141, v186
	v_lshlrev_b32_e32 v186, 1, v185
	v_add_u32_e32 v186, 0xd800, v186
	v_add_u32_e32 v175, v142, v186
	v_add_u32_e32 v176, v143, v186
	v_add_u32_e32 v177, v144, v186
	v_add_u32_e32 v178, v145, v186
	v_sub_u32_e32 v187, v134, v185
	v_cvt_f32_u32_e32 v179, v187
	s_mov_b32 s11, s58

; #define LAS __attribute__((address_space(3)))
; __device__ void attn_mfma(const Params& p, int l, const bf16_t* proj, bf16_t* y0, LAS unsigned char* lds) {
;     ...
;             for (int q = 0; q < 6; ++q) { const int c = tid + q * NTHREADS, row = c >> 3, part = c & 7; *(LAS u32x4*)(Ks + row * KP + part * 8) = kreg[q]; }
; #pragma unroll
;             for (int q = 0; q < 3; ++q) { const int c = tid + q * NTHREADS, pr = c >> 3, part = c & 7; const u32x4 a = va[q], b = vb[q];
; #pragma unroll
;                 for (int e = 0; e < 4; ++e) {
;                     *(LAS unsigned*)(Vt + (part * 8 + 2 * e) * VP + pr * 2) = (a[e] & 0xffffu) | (b[e] << 16);
;                     *(LAS unsigned*)(Vt + (part * 8 + 2 * e + 1) * VP + pr * 2) = (a[e] >> 16) | (b[e] & 0xffff0000u); } }
;         }
;         const int hq = hk * 4 + (wv >> 1);
;         bf16x8 qn[2];
; #pragma unroll
;         for (int ks = 0; ks < 2; ++ks) qn[ks] = *(const bf16x8*)(proj + (size_t)(n * 128 + (wv & 1) * 64 + fr) * NP + AQ + hq * 64 + ks * 32 + g * 8);
;         __syncthreads();
;         const float slope = exp2f(-(float)(hq + 1)), sink = p.attn_sink[l * 8 + hq];
;         const bool edge = (n == 0) || (n == SEQ / 128 - 1);
.LBB0_477:
	s_or_b64 exec, exec, s[4:5]
	s_waitcnt vmcnt(0)
	ds_write_b128 v135, v[4:7]
	ds_write_b128 v136, v[0:3]
	ds_write_b128 v137, v[12:15]
	ds_write_b128 v138, v[8:11]
	ds_write_b128 v139, v[20:23]
	ds_write_b128 v140, v[16:19]
	v_and_b32_e32 v0, 0xffff, v28
	v_lshrrev_b32_e32 v1, 16, v28
	v_lshl_or_b32 v0, v32, 16, v0
	v_and_or_b32 v1, v32, s0, v1
	v_add_u32_e32 v2, 0xd800, v131
	ds_write2_b32 v2, v0, v1 offset1:196
	v_and_b32_e32 v0, 0xffff, v29
	v_lshrrev_b32_e32 v1, 16, v29
	v_lshl_or_b32 v0, v33, 16, v0
	v_and_or_b32 v1, v33, s0, v1
	v_add_u32_e32 v2, 0xde00, v131
	ds_write2_b32 v2, v0, v1 offset0:8 offset1:204
	v_and_b32_e32 v0, 0xffff, v30
	v_lshrrev_b32_e32 v1, 16, v30
	v_lshl_or_b32 v0, v34, 16, v0
	v_and_or_b32 v1, v34, s0, v1
	v_add_u32_e32 v2, 0xe400, v131
	ds_write2_b32 v2, v0, v1 offset0:16 offset1:212
	v_and_b32_e32 v0, 0xffff, v31
	v_lshrrev_b32_e32 v1, 16, v31
	v_lshl_or_b32 v0, v35, 16, v0
	v_and_or_b32 v1, v35, s0, v1
	v_add_u32_e32 v2, 0xea00, v131
	ds_write2_b32 v2, v0, v1 offset0:24 offset1:220
	v_and_b32_e32 v0, 0xffff, v24
	v_lshrrev_b32_e32 v1, 16, v24
	v_lshl_or_b32 v0, v36, 16, v0
	v_and_or_b32 v1, v36, s0, v1
	v_add_u32_e32 v2, 0xd800, v132
	ds_write2_b32 v2, v0, v1 offset1:196
	v_and_b32_e32 v0, 0xffff, v25
	v_lshrrev_b32_e32 v1, 16, v25
	v_lshl_or_b32 v0, v37, 16, v0
	v_and_or_b32 v1, v37, s0, v1
	v_add_u32_e32 v2, 0xde00, v132
	ds_write2_b32 v2, v0, v1 offset0:8 offset1:204
	v_and_b32_e32 v0, 0xffff, v26
	v_lshrrev_b32_e32 v1, 16, v26
	v_lshl_or_b32 v0, v38, 16, v0
	v_and_or_b32 v1, v38, s0, v1
	v_add_u32_e32 v2, 0xe400, v132
	ds_write2_b32 v2, v0, v1 offset0:16 offset1:212
	v_and_b32_e32 v0, 0xffff, v27
	v_lshrrev_b32_e32 v1, 16, v27
	v_lshl_or_b32 v0, v39, 16, v0
	v_and_or_b32 v1, v39, s0, v1
	v_add_u32_e32 v2, 0xea00, v132
	ds_write2_b32 v2, v0, v1 offset0:24 offset1:220
	v_and_b32_e32 v0, 0xffff, v40
	v_lshrrev_b32_e32 v1, 16, v40
	v_lshl_or_b32 v0, v44, 16, v0
	v_and_or_b32 v1, v44, s0, v1
	v_add_u32_e32 v2, 0xd800, v133
	ds_write2_b32 v2, v0, v1 offset1:196
	v_and_b32_e32 v0, 0xffff, v41
	v_lshrrev_b32_e32 v1, 16, v41
	v_lshl_or_b32 v0, v45, 16, v0
	v_and_or_b32 v1, v45, s0, v1
	v_add_u32_e32 v2, 0xde00, v133
	ds_write2_b32 v2, v0, v1 offset0:8 offset1:204
	v_and_b32_e32 v0, 0xffff, v42
	v_lshrrev_b32_e32 v1, 16, v42
	v_lshl_or_b32 v0, v46, 16, v0
	v_and_or_b32 v1, v46, s0, v1
	v_add_u32_e32 v2, 0xe400, v133
	ds_write2_b32 v2, v0, v1 offset0:16 offset1:212
	v_and_b32_e32 v0, 0xffff, v43
	v_lshrrev_b32_e32 v1, 16, v43
	v_lshl_add_u32 v6, s6, 2, v109
	v_lshl_or_b32 v0, v47, 16, v0
	v_and_or_b32 v1, v47, s0, v1
	v_add_u32_e32 v2, 0xea00, v133
	v_lshlrev_b32_e32 v114, 6, v6
	ds_write2_b32 v2, v0, v1 offset0:24 offset1:220
	v_or_b32_e32 v2, s13, v120
	v_mov_b64_e32 v[0:1], s[94:95]
	v_ashrrev_i32_e32 v115, 31, v114
	v_mad_i64_i32 v[0:1], s[4:5], v2, s63, v[0:1]
	v_lshlrev_b64 v[2:3], 1, v[114:115]
	v_lshl_add_u64 v[0:1], v[0:1], 0, v[2:3]
	v_lshlrev_b32_e32 v188, 1, v110
	v_lshl_add_u64 v[0:1], v[0:1], 0, v[188:189]
	v_lshl_add_u64 v[4:5], v[0:1], 0, s[24:25]
	v_add_co_u32_e32 v0, vcc, s66, v0
	v_readlane_b32 s40, v254, 48
	s_nop 0
	v_addc_co_u32_e32 v1, vcc, 0, v1, vcc
	global_load_dwordx4 v[100:103], v[0:1], off offset:2048
	global_load_dwordx4 v[8:11], v[4:5], off offset:64
	v_add_u32_e32 v0, s10, v6
	v_ashrrev_i32_e32 v1, 31, v0
	v_readlane_b32 s44, v254, 52
	v_readlane_b32 s45, v254, 53
	s_waitcnt lgkmcnt(0)
	s_barrier
	v_lshl_add_u64 v[0:1], v[0:1], 2, s[44:45]
	global_load_dword v146, v[0:1], off
	v_add_u32_e32 v0, 1, v6
	v_cvt_f32_i32_e32 v0, v0
	s_mov_b32 s4, 0x42fc0000
	s_cmp_gt_u32 s11, 1
	s_mov_b32 s12, 0
	v_cmp_lt_f32_e32 vcc, s4, v0
	s_cselect_b64 s[4:5], -1, 0
	s_cselect_b32 s16, s71, 0xbf800000
	s_cmp_lt_u32 s11, 2
	v_cndmask_b32_e32 v1, 0, v218, vcc
	v_sub_f32_e32 v0, v1, v0
	v_exp_f32_e32 v0, v0
	s_cselect_b64 s[6:7], -1, 0
	s_cmpk_lg_i32 s8, 0x7f
	s_cselect_b32 s17, s71, 0xbf800000
	v_cndmask_b32_e32 v1, 0, v219, vcc
	s_cselect_b64 s[8:9], -1, 0
	v_ldexp_f32 v147, v0, v1
	v_mul_f32_e32 v147, 0x41000000, v147
	s_and_b64 s[8:9], s[4:5], s[8:9]
	v_lshl_add_u64 v[116:117], v[112:113], 0, v[2:3]
	v_add_u32_e32 v148, s13, v120
	v_readlane_b32 s41, v254, 49
	v_readlane_b32 s42, v254, 50
	v_readlane_b32 s43, v254, 51
	v_readlane_b32 s46, v254, 54
	v_readlane_b32 s47, v254, 55
	v_readlane_b32 s48, v254, 56
	v_readlane_b32 s49, v254, 57
	v_readlane_b32 s50, v254, 58
	v_readlane_b32 s51, v254, 59
	v_readlane_b32 s52, v254, 60
	v_readlane_b32 s53, v254, 61
	v_readlane_b32 s54, v254, 62
	v_readlane_b32 s55, v254, 63
	s_waitcnt vmcnt(0)
	v_readfirstlane_b32 s9, v120
	s_and_b32 s9, s9, 64
	s_lshr_b32 s9, s9, 4
; #define LAS __attribute__((address_space(3)))
; __device__ void attn_mfma(const Params& p, int l, const bf16_t* proj, bf16_t* y0, LAS unsigned char* lds) {
;     ...
;         for (int tile = 0; tile < 4; ++tile) {
;             const int tl = (wv & 1) * 64 + tile * 16 + fr, t = n * 128 + tl;
;             bf16x8 qf[2];
; #pragma unroll
;             for (int ks = 0; ks < 2; ++ks) { qf[ks] = qn[ks]; qn[ks] = *(const bf16x8*)(proj + (size_t)(t + (tile < 3 ? 16 : 0)) * NP + AQ + hq * 64 + ks * 32 + g * 8); }
;             f32x4 sacc[24];
; #pragma unroll
;             for (int kt = 0; kt < 24; ++kt) { f32x4 a = {0.f, 0.f, 0.f, 0.f};
; #pragma unroll
;                 for (int ks = 0; ks < 2; ++ks) { const bf16x8 kf = *(const LAS bf16x8*)(Ks + (kt * 16 + fr) * KP + ks * 32 + g * 8); a = __builtin_amdgcn_mfma_f32_16x16x32_bf16(kf, qf[ks], a, 0, 0, 0); }
;                 sacc[kt] = a; if ((kt % 6) == 5) __builtin_amdgcn_sched_barrier(0); }
.LBB0_478:
	s_mul_i32 s7, s12, 0x90
	s_lshl_b32 s5, s12, 1
	v_add_u32_e32 v180, s7, v174
	v_add_u32_e32 v181, s5, v175
	v_add_u32_e32 v182, s5, v176
	v_add_u32_e32 v183, s5, v177
	v_add_u32_e32 v184, s5, v178
	s_lshr_b32 s4, s12, 4
	s_add_i32 s4, s4, s9
	ds_read_b128 v[12:15], v180 offset:0
	ds_read_b128 v[80:83], v180 offset:64
	ds_read_b128 v[16:19], v180 offset:2304
	ds_read_b128 v[84:87], v180 offset:2368
	ds_read_b128 v[20:23], v180 offset:4608
	ds_read_b128 v[88:91], v180 offset:4672
	ds_read_b128 v[24:27], v180 offset:6912
	ds_read_b128 v[92:95], v180 offset:6976
	ds_read_b128 v[28:31], v180 offset:9216
	ds_read_b128 v[96:99], v180 offset:9280
	ds_read_b128 v[32:35], v180 offset:11520
	ds_read_b128 v[104:107], v180 offset:11584
	v_add_u32_e32 v118, s12, v148
	s_cmp_eq_u32 s12, 48
	s_cselect_b32 s13, 0, 16
	v_add_u32_e32 v162, s13, v118
	v_mov_b64_e32 v[160:161], s[94:95]
	v_mad_i64_i32 v[168:169], s[14:15], v162, s63, v[160:161]
	v_lshl_add_u64 v[160:161], v[114:115], 1, v[168:169]
	v_lshl_add_u64 v[162:163], v[160:161], 0, v[188:189]
	v_add_co_u32_e32 v164, vcc, 0x1000, v162
	v_lshl_add_u64 v[166:167], v[162:163], 0, s[24:25]
	s_nop 0
	v_addc_co_u32_e32 v165, vcc, 0, v163, vcc
	global_load_dwordx4 v[0:3], v[164:165], off offset:2048
	global_load_dwordx4 v[4:7], v[166:167], off offset:64
	s_waitcnt lgkmcnt(11)
	v_mfma_f32_16x16x32_bf16 v[12:15], v[12:15], v[100:103], 0
	s_waitcnt lgkmcnt(10)
	v_mfma_f32_16x16x32_bf16 v[12:15], v[80:83], v[8:11], v[12:15]
	ds_read_b128 v[36:39], v180 offset:13824
	ds_read_b128 v[80:83], v180 offset:13888
	s_waitcnt lgkmcnt(11)
	v_mfma_f32_16x16x32_bf16 v[16:19], v[16:19], v[100:103], 0
	s_waitcnt lgkmcnt(10)
	v_mfma_f32_16x16x32_bf16 v[16:19], v[84:87], v[8:11], v[16:19]
	ds_read_b128 v[40:43], v180 offset:16128
	ds_read_b128 v[84:87], v180 offset:16192
	s_waitcnt lgkmcnt(11)
	v_mfma_f32_16x16x32_bf16 v[20:23], v[20:23], v[100:103], 0
	s_waitcnt lgkmcnt(10)
	v_mfma_f32_16x16x32_bf16 v[20:23], v[88:91], v[8:11], v[20:23]
	ds_read_b128 v[44:47], v180 offset:18432
	ds_read_b128 v[88:91], v180 offset:18496
	s_waitcnt lgkmcnt(11)
	v_mfma_f32_16x16x32_bf16 v[24:27], v[24:27], v[100:103], 0
	s_waitcnt lgkmcnt(10)
	v_mfma_f32_16x16x32_bf16 v[24:27], v[92:95], v[8:11], v[24:27]
	ds_read_b128 v[48:51], v180 offset:20736
	ds_read_b128 v[92:95], v180 offset:20800
	s_waitcnt lgkmcnt(11)
	v_mfma_f32_16x16x32_bf16 v[28:31], v[28:31], v[100:103], 0
	s_waitcnt lgkmcnt(10)
	v_mfma_f32_16x16x32_bf16 v[28:31], v[96:99], v[8:11], v[28:31]
	ds_read_b128 v[52:55], v180 offset:23040
	ds_read_b128 v[96:99], v180 offset:23104
	s_waitcnt lgkmcnt(11)
	v_mfma_f32_16x16x32_bf16 v[32:35], v[32:35], v[100:103], 0
	s_waitcnt lgkmcnt(10)
	v_mfma_f32_16x16x32_bf16 v[32:35], v[104:107], v[8:11], v[32:35]
	ds_read_b128 v[56:59], v180 offset:25344
	ds_read_b128 v[104:107], v180 offset:25408
	s_waitcnt lgkmcnt(11)
	v_mfma_f32_16x16x32_bf16 v[36:39], v[36:39], v[100:103], 0
	s_waitcnt lgkmcnt(10)
	v_mfma_f32_16x16x32_bf16 v[36:39], v[80:83], v[8:11], v[36:39]
	ds_read_b128 v[60:63], v180 offset:27648
	ds_read_b128 v[80:83], v180 offset:27712
	s_waitcnt lgkmcnt(11)
	v_mfma_f32_16x16x32_bf16 v[40:43], v[40:43], v[100:103], 0
	s_waitcnt lgkmcnt(10)
	v_mfma_f32_16x16x32_bf16 v[40:43], v[84:87], v[8:11], v[40:43]
	ds_read_b128 v[64:67], v180 offset:29952
	ds_read_b128 v[84:87], v180 offset:30016
	s_waitcnt lgkmcnt(11)
	v_mfma_f32_16x16x32_bf16 v[44:47], v[44:47], v[100:103], 0
	s_waitcnt lgkmcnt(10)
	v_mfma_f32_16x16x32_bf16 v[44:47], v[88:91], v[8:11], v[44:47]
	ds_read_b128 v[68:71], v180 offset:32256
	ds_read_b128 v[88:91], v180 offset:32320
	s_waitcnt lgkmcnt(11)
	v_mfma_f32_16x16x32_bf16 v[48:51], v[48:51], v[100:103], 0
	s_waitcnt lgkmcnt(10)
	v_mfma_f32_16x16x32_bf16 v[48:51], v[92:95], v[8:11], v[48:51]
	ds_read_b128 v[72:75], v180 offset:34560
	ds_read_b128 v[92:95], v180 offset:34624
	s_waitcnt lgkmcnt(11)
	v_mfma_f32_16x16x32_bf16 v[52:55], v[52:55], v[100:103], 0
	s_waitcnt lgkmcnt(10)
	v_mfma_f32_16x16x32_bf16 v[52:55], v[96:99], v[8:11], v[52:55]
	ds_read_b128 v[76:79], v180 offset:36864
	ds_read_b128 v[96:99], v180 offset:36928
	s_waitcnt lgkmcnt(11)
	v_mfma_f32_16x16x32_bf16 v[56:59], v[56:59], v[100:103], 0
	s_waitcnt lgkmcnt(10)
	v_mfma_f32_16x16x32_bf16 v[56:59], v[104:107], v[8:11], v[56:59]
	s_waitcnt lgkmcnt(9)
	v_mfma_f32_16x16x32_bf16 v[60:63], v[60:63], v[100:103], 0
	s_waitcnt lgkmcnt(8)
	v_mfma_f32_16x16x32_bf16 v[60:63], v[80:83], v[8:11], v[60:63]
	s_waitcnt lgkmcnt(7)
	v_mfma_f32_16x16x32_bf16 v[64:67], v[64:67], v[100:103], 0
	s_waitcnt lgkmcnt(6)
	v_mfma_f32_16x16x32_bf16 v[64:67], v[84:87], v[8:11], v[64:67]
	s_waitcnt lgkmcnt(5)
	v_mfma_f32_16x16x32_bf16 v[68:71], v[68:71], v[100:103], 0
	s_waitcnt lgkmcnt(4)
	v_mfma_f32_16x16x32_bf16 v[68:71], v[88:91], v[8:11], v[68:71]
	s_waitcnt lgkmcnt(3)
	v_mfma_f32_16x16x32_bf16 v[72:75], v[72:75], v[100:103], 0
	s_waitcnt lgkmcnt(2)
	v_mfma_f32_16x16x32_bf16 v[72:75], v[92:95], v[8:11], v[72:75]
	s_waitcnt lgkmcnt(1)
	v_mfma_f32_16x16x32_bf16 v[76:79], v[76:79], v[100:103], 0
	s_waitcnt lgkmcnt(0)
; __device__ void attn_mfma(const Params& p, int l, const bf16_t* proj, bf16_t* y0, LAS unsigned char* lds) {
;     ...
;                 sacc[kt] = a; if ((kt % 6) == 5) __builtin_amdgcn_sched_barrier(0); }
;             const float tq = (float)(tl + 128 - 4 * g);
;             float mx = sink;
; #pragma unroll
;             for (int kt = 0; kt < 24; ++kt)
; #pragma unroll
;                 for (int r = 0; r < 4; ++r) { const float x = (float)(kt * 16 + r) - tq; float sc = fmaf(sacc[kt][r], 0.125f, -slope * fabsf(x));
;                     bool valid = fabsf(x) <= 128.0f;
;                     if (edge) { const int kl = kt * 16 + 4 * g + r; valid = valid && (n == 0 ? kl >= 128 : kl < 256); }
;                     sc = valid ? sc : -1e30f; sacc[kt][r] = sc; mx = fmaxf(mx, sc); }
	v_mfma_f32_16x16x32_bf16 v[76:79], v[96:99], v[8:11], v[76:79]
	v_mul_f32_e32 v154, 0x41000000, v146
	s_cmp_lt_i32 s4, 8
	s_cselect_b32 s5, s16, s71
	v_sub_f32_e32 v150, 0, v179
	v_sub_f32_e32 v151, 1.0, v179
	v_sub_f32_e32 v152, 2.0, v179
	v_sub_f32_e32 v153, 0x40400000, v179
	s_nop 4
	v_cmp_le_f32_e64 vcc, |v150|, s5
	v_fma_f32 v12, |v150|, -v147, v12
	v_cmp_le_f32_e64 s[14:15], |v151|, s5
	v_cndmask_b32_e32 v12, v220, v12, vcc
	v_fma_f32 v13, |v151|, -v147, v13
	v_cmp_le_f32_e64 vcc, |v152|, s5
	v_cndmask_b32_e64 v13, v220, v13, s[14:15]
	v_fma_f32 v14, |v152|, -v147, v14
	v_cmp_le_f32_e64 s[14:15], |v153|, s5
	v_cndmask_b32_e32 v14, v220, v14, vcc
	v_fma_f32 v15, |v153|, -v147, v15
	v_max3_f32 v154, v154, v12, v13
	v_cndmask_b32_e64 v15, v220, v15, s[14:15]
	v_max3_f32 v154, v154, v14, v15
	s_cmp_lt_i32 s4, 7
	s_cselect_b32 s6, s16, s71
	v_sub_f32_e32 v150, 0x41800000, v179
	v_sub_f32_e32 v151, 0x41880000, v179
	v_sub_f32_e32 v152, 0x41900000, v179
	v_sub_f32_e32 v153, 0x41980000, v179
	v_cmp_le_f32_e64 vcc, |v150|, s6
	v_fma_f32 v16, |v150|, -v147, v16
	v_cmp_le_f32_e64 s[14:15], |v151|, s6
	v_cndmask_b32_e32 v16, v220, v16, vcc
	v_fma_f32 v17, |v151|, -v147, v17
	v_cmp_le_f32_e64 vcc, |v152|, s6
	v_cndmask_b32_e64 v17, v220, v17, s[14:15]
	v_fma_f32 v18, |v152|, -v147, v18
	v_cmp_le_f32_e64 s[14:15], |v153|, s6
	v_cndmask_b32_e32 v18, v220, v18, vcc
	v_fma_f32 v19, |v153|, -v147, v19
	v_max3_f32 v154, v154, v16, v17
	v_cndmask_b32_e64 v19, v220, v19, s[14:15]
	v_max3_f32 v154, v154, v18, v19
	s_cmp_lt_i32 s4, 6
	s_cselect_b32 s5, s16, s71
	v_sub_f32_e32 v150, 0x42000000, v179
	v_sub_f32_e32 v151, 0x42040000, v179
	v_sub_f32_e32 v152, 0x42080000, v179
	v_sub_f32_e32 v153, 0x420c0000, v179
	v_cmp_le_f32_e64 vcc, |v150|, s5
	v_fma_f32 v20, |v150|, -v147, v20
	v_cmp_le_f32_e64 s[14:15], |v151|, s5
	v_cndmask_b32_e32 v20, v220, v20, vcc
	v_fma_f32 v21, |v151|, -v147, v21
	v_cmp_le_f32_e64 vcc, |v152|, s5
	v_cndmask_b32_e64 v21, v220, v21, s[14:15]
	v_fma_f32 v22, |v152|, -v147, v22
	v_cmp_le_f32_e64 s[14:15], |v153|, s5
	v_cndmask_b32_e32 v22, v220, v22, vcc
	v_fma_f32 v23, |v153|, -v147, v23
	v_max3_f32 v154, v154, v20, v21
	v_cndmask_b32_e64 v23, v220, v23, s[14:15]
	v_max3_f32 v154, v154, v22, v23
	s_cmp_lt_i32 s4, 5
	s_cselect_b32 s6, s16, s71
	v_sub_f32_e32 v150, 0x42400000, v179
	v_sub_f32_e32 v151, 0x42440000, v179
	v_sub_f32_e32 v152, 0x42480000, v179
	v_sub_f32_e32 v153, 0x424c0000, v179
	v_cmp_le_f32_e64 vcc, |v150|, s6
	v_fma_f32 v24, |v150|, -v147, v24
	v_cmp_le_f32_e64 s[14:15], |v151|, s6
	v_cndmask_b32_e32 v24, v220, v24, vcc
	v_fma_f32 v25, |v151|, -v147, v25
	v_cmp_le_f32_e64 vcc, |v152|, s6
	v_cndmask_b32_e64 v25, v220, v25, s[14:15]
	v_fma_f32 v26, |v152|, -v147, v26
	v_cmp_le_f32_e64 s[14:15], |v153|, s6
	v_cndmask_b32_e32 v26, v220, v26, vcc
	v_fma_f32 v27, |v153|, -v147, v27
	v_max3_f32 v154, v154, v24, v25
	v_cndmask_b32_e64 v27, v220, v27, s[14:15]
	v_max3_f32 v154, v154, v26, v27
	s_cmp_lt_i32 s4, 4
	s_cselect_b32 s5, s16, s71
	v_sub_f32_e32 v150, 0x42800000, v179
	v_sub_f32_e32 v151, 0x42820000, v179
	v_sub_f32_e32 v152, 0x42840000, v179
	v_sub_f32_e32 v153, 0x42860000, v179
	v_cmp_le_f32_e64 vcc, |v150|, s5
	v_fma_f32 v28, |v150|, -v147, v28
	v_cmp_le_f32_e64 s[14:15], |v151|, s5
	v_cndmask_b32_e32 v28, v220, v28, vcc
	v_fma_f32 v29, |v151|, -v147, v29
	v_cmp_le_f32_e64 vcc, |v152|, s5
	v_cndmask_b32_e64 v29, v220, v29, s[14:15]
	v_fma_f32 v30, |v152|, -v147, v30
	v_cmp_le_f32_e64 s[14:15], |v153|, s5
	v_cndmask_b32_e32 v30, v220, v30, vcc
	v_fma_f32 v31, |v153|, -v147, v31
	v_max3_f32 v154, v154, v28, v29
	v_cndmask_b32_e64 v31, v220, v31, s[14:15]
	v_max3_f32 v154, v154, v30, v31
	s_cmp_lt_i32 s4, 3
	s_cselect_b32 s6, s16, s71
	v_sub_f32_e32 v150, 0x42a00000, v179
	v_sub_f32_e32 v151, 0x42a20000, v179
	v_sub_f32_e32 v152, 0x42a40000, v179
	v_sub_f32_e32 v153, 0x42a60000, v179
	v_cmp_le_f32_e64 vcc, |v150|, s6
	v_fma_f32 v32, |v150|, -v147, v32
	v_cmp_le_f32_e64 s[14:15], |v151|, s6
	v_cndmask_b32_e32 v32, v220, v32, vcc
	v_fma_f32 v33, |v151|, -v147, v33
	v_cmp_le_f32_e64 vcc, |v152|, s6
	v_cndmask_b32_e64 v33, v220, v33, s[14:15]
	v_fma_f32 v34, |v152|, -v147, v34
	v_cmp_le_f32_e64 s[14:15], |v153|, s6
	v_cndmask_b32_e32 v34, v220, v34, vcc
	v_fma_f32 v35, |v153|, -v147, v35
	v_max3_f32 v154, v154, v32, v33
	v_cndmask_b32_e64 v35, v220, v35, s[14:15]
	v_max3_f32 v154, v154, v34, v35
	s_cmp_lt_i32 s4, 2
	s_cselect_b32 s5, s16, s71
	v_sub_f32_e32 v150, 0x42c00000, v179
	v_sub_f32_e32 v151, 0x42c20000, v179
	v_sub_f32_e32 v152, 0x42c40000, v179
	v_sub_f32_e32 v153, 0x42c60000, v179
	v_cmp_le_f32_e64 vcc, |v150|, s5
	v_fma_f32 v36, |v150|, -v147, v36
	v_cmp_le_f32_e64 s[14:15], |v151|, s5
	v_cndmask_b32_e32 v36, v220, v36, vcc
	v_fma_f32 v37, |v151|, -v147, v37
	v_cmp_le_f32_e64 vcc, |v152|, s5
	v_cndmask_b32_e64 v37, v220, v37, s[14:15]
	v_fma_f32 v38, |v152|, -v147, v38
	v_cmp_le_f32_e64 s[14:15], |v153|, s5
	v_cndmask_b32_e32 v38, v220, v38, vcc
	v_fma_f32 v39, |v153|, -v147, v39
	v_max3_f32 v154, v154, v36, v37
	v_cndmask_b32_e64 v39, v220, v39, s[14:15]
	v_max3_f32 v154, v154, v38, v39
	s_cmp_lt_i32 s4, 1
	s_cselect_b32 s6, s16, s71
	v_sub_f32_e32 v150, 0x42e00000, v179
	v_sub_f32_e32 v151, 0x42e20000, v179
	v_sub_f32_e32 v152, 0x42e40000, v179
	v_sub_f32_e32 v153, 0x42e60000, v179
	v_cmp_le_f32_e64 vcc, |v150|, s6
	v_fma_f32 v40, |v150|, -v147, v40
	v_cmp_le_f32_e64 s[14:15], |v151|, s6
	v_cndmask_b32_e32 v40, v220, v40, vcc
	v_fma_f32 v41, |v151|, -v147, v41
	v_cmp_le_f32_e64 vcc, |v152|, s6
	v_cndmask_b32_e64 v41, v220, v41, s[14:15]
	v_fma_f32 v42, |v152|, -v147, v42
	v_cmp_le_f32_e64 s[14:15], |v153|, s6
; __device__ void attn_mfma(const Params& p, int l, const bf16_t* proj, bf16_t* y0, LAS unsigned char* lds) {
;     ...
;             for (int kt = 0; kt < 24; ++kt)
; #pragma unroll
;                 for (int r = 0; r < 4; ++r) { const float x = (float)(kt * 16 + r) - tq; float sc = fmaf(sacc[kt][r], 0.125f, -slope * fabsf(x));
;                     bool valid = fabsf(x) <= 128.0f;
;                     if (edge) { const int kl = kt * 16 + 4 * g + r; valid = valid && (n == 0 ? kl >= 128 : kl < 256); }
;                     sc = valid ? sc : -1e30f; sacc[kt][r] = sc; mx = fmaxf(mx, sc); }
	v_cndmask_b32_e32 v42, v220, v42, vcc
	v_fma_f32 v43, |v153|, -v147, v43
	v_max3_f32 v154, v154, v40, v41
	v_cndmask_b32_e64 v43, v220, v43, s[14:15]
	v_max3_f32 v154, v154, v42, v43
	v_sub_f32_e32 v150, 0x43000000, v179
	v_sub_f32_e32 v151, 0x43010000, v179
	v_sub_f32_e32 v152, 0x43020000, v179
	v_sub_f32_e32 v153, 0x43030000, v179
	v_cmp_le_f32_e64 vcc, |v150|, s71
	v_fma_f32 v44, |v150|, -v147, v44
	v_cmp_le_f32_e64 s[14:15], |v151|, s71
	v_cndmask_b32_e32 v44, v220, v44, vcc
	v_fma_f32 v45, |v151|, -v147, v45
	v_cmp_le_f32_e64 vcc, |v152|, s71
	v_cndmask_b32_e64 v45, v220, v45, s[14:15]
	v_fma_f32 v46, |v152|, -v147, v46
	v_cmp_le_f32_e64 s[14:15], |v153|, s71
	v_cndmask_b32_e32 v46, v220, v46, vcc
	v_fma_f32 v47, |v153|, -v147, v47
	v_max3_f32 v154, v154, v44, v45
	v_cndmask_b32_e64 v47, v220, v47, s[14:15]
	v_max3_f32 v154, v154, v46, v47
	s_cmp_ge_i32 s4, 7
	s_cselect_b32 s6, s17, s71
	v_sub_f32_e32 v150, 0x43100000, v179
	v_sub_f32_e32 v151, 0x43110000, v179
	v_sub_f32_e32 v152, 0x43120000, v179
	v_sub_f32_e32 v153, 0x43130000, v179
	v_cmp_le_f32_e64 vcc, |v150|, s6
	v_fma_f32 v48, |v150|, -v147, v48
	v_cmp_le_f32_e64 s[14:15], |v151|, s6
	v_cndmask_b32_e32 v48, v220, v48, vcc
	v_fma_f32 v49, |v151|, -v147, v49
	v_cmp_le_f32_e64 vcc, |v152|, s6
	v_cndmask_b32_e64 v49, v220, v49, s[14:15]
	v_fma_f32 v50, |v152|, -v147, v50
	v_cmp_le_f32_e64 s[14:15], |v153|, s6
	v_cndmask_b32_e32 v50, v220, v50, vcc
	v_fma_f32 v51, |v153|, -v147, v51
	v_max3_f32 v154, v154, v48, v49
	v_cndmask_b32_e64 v51, v220, v51, s[14:15]
	v_max3_f32 v154, v154, v50, v51
	s_cmp_ge_i32 s4, 6
	s_cselect_b32 s5, s17, s71
	v_sub_f32_e32 v150, 0x43200000, v179
	v_sub_f32_e32 v151, 0x43210000, v179
	v_sub_f32_e32 v152, 0x43220000, v179
	v_sub_f32_e32 v153, 0x43230000, v179
	v_cmp_le_f32_e64 vcc, |v150|, s5
	v_fma_f32 v52, |v150|, -v147, v52
	v_cmp_le_f32_e64 s[14:15], |v151|, s5
	v_cndmask_b32_e32 v52, v220, v52, vcc
	v_fma_f32 v53, |v151|, -v147, v53
	v_cmp_le_f32_e64 vcc, |v152|, s5
	v_cndmask_b32_e64 v53, v220, v53, s[14:15]
	v_fma_f32 v54, |v152|, -v147, v54
	v_cmp_le_f32_e64 s[14:15], |v153|, s5
	v_cndmask_b32_e32 v54, v220, v54, vcc
	v_fma_f32 v55, |v153|, -v147, v55
	v_max3_f32 v154, v154, v52, v53
	v_cndmask_b32_e64 v55, v220, v55, s[14:15]
	v_max3_f32 v154, v154, v54, v55
	s_cmp_ge_i32 s4, 5
	s_cselect_b32 s6, s17, s71
	v_sub_f32_e32 v150, 0x43300000, v179
	v_sub_f32_e32 v151, 0x43310000, v179
	v_sub_f32_e32 v152, 0x43320000, v179
	v_sub_f32_e32 v153, 0x43330000, v179
	v_cmp_le_f32_e64 vcc, |v150|, s6
	v_fma_f32 v56, |v150|, -v147, v56
	v_cmp_le_f32_e64 s[14:15], |v151|, s6
	v_cndmask_b32_e32 v56, v220, v56, vcc
	v_fma_f32 v57, |v151|, -v147, v57
	v_cmp_le_f32_e64 vcc, |v152|, s6
	v_cndmask_b32_e64 v57, v220, v57, s[14:15]
	v_fma_f32 v58, |v152|, -v147, v58
	v_cmp_le_f32_e64 s[14:15], |v153|, s6
	v_cndmask_b32_e32 v58, v220, v58, vcc
	v_fma_f32 v59, |v153|, -v147, v59
	v_max3_f32 v154, v154, v56, v57
	v_cndmask_b32_e64 v59, v220, v59, s[14:15]
	v_max3_f32 v154, v154, v58, v59
	s_cmp_ge_i32 s4, 4
	s_cselect_b32 s5, s17, s71
	v_sub_f32_e32 v150, 0x43400000, v179
	v_sub_f32_e32 v151, 0x43410000, v179
	v_sub_f32_e32 v152, 0x43420000, v179
	v_sub_f32_e32 v153, 0x43430000, v179
	v_cmp_le_f32_e64 vcc, |v150|, s5
	v_fma_f32 v60, |v150|, -v147, v60
	v_cmp_le_f32_e64 s[14:15], |v151|, s5
	v_cndmask_b32_e32 v60, v220, v60, vcc
	v_fma_f32 v61, |v151|, -v147, v61
	v_cmp_le_f32_e64 vcc, |v152|, s5
	v_cndmask_b32_e64 v61, v220, v61, s[14:15]
	v_fma_f32 v62, |v152|, -v147, v62
	v_cmp_le_f32_e64 s[14:15], |v153|, s5
	v_cndmask_b32_e32 v62, v220, v62, vcc
	v_fma_f32 v63, |v153|, -v147, v63
	v_max3_f32 v154, v154, v60, v61
	v_cndmask_b32_e64 v63, v220, v63, s[14:15]
	v_max3_f32 v154, v154, v62, v63
	s_cmp_ge_i32 s4, 3
	s_cselect_b32 s6, s17, s71
	v_sub_f32_e32 v150, 0x43500000, v179
	v_sub_f32_e32 v151, 0x43510000, v179
	v_sub_f32_e32 v152, 0x43520000, v179
	v_sub_f32_e32 v153, 0x43530000, v179
	v_cmp_le_f32_e64 vcc, |v150|, s6
	v_fma_f32 v64, |v150|, -v147, v64
	v_cmp_le_f32_e64 s[14:15], |v151|, s6
	v_cndmask_b32_e32 v64, v220, v64, vcc
	v_fma_f32 v65, |v151|, -v147, v65
	v_cmp_le_f32_e64 vcc, |v152|, s6
	v_cndmask_b32_e64 v65, v220, v65, s[14:15]
	v_fma_f32 v66, |v152|, -v147, v66
	v_cmp_le_f32_e64 s[14:15], |v153|, s6
	v_cndmask_b32_e32 v66, v220, v66, vcc
	v_fma_f32 v67, |v153|, -v147, v67
	v_max3_f32 v154, v154, v64, v65
	v_cndmask_b32_e64 v67, v220, v67, s[14:15]
	v_max3_f32 v154, v154, v66, v67
	s_cmp_ge_i32 s4, 2
	s_cselect_b32 s5, s17, s71
	v_sub_f32_e32 v150, 0x43600000, v179
	v_sub_f32_e32 v151, 0x43610000, v179
	v_sub_f32_e32 v152, 0x43620000, v179
	v_sub_f32_e32 v153, 0x43630000, v179
	v_cmp_le_f32_e64 vcc, |v150|, s5
	v_fma_f32 v68, |v150|, -v147, v68
	v_cmp_le_f32_e64 s[14:15], |v151|, s5
	v_cndmask_b32_e32 v68, v220, v68, vcc
	v_fma_f32 v69, |v151|, -v147, v69
	v_cmp_le_f32_e64 vcc, |v152|, s5
	v_cndmask_b32_e64 v69, v220, v69, s[14:15]
	v_fma_f32 v70, |v152|, -v147, v70
	v_cmp_le_f32_e64 s[14:15], |v153|, s5
	v_cndmask_b32_e32 v70, v220, v70, vcc
	v_fma_f32 v71, |v153|, -v147, v71
	v_max3_f32 v154, v154, v68, v69
	v_cndmask_b32_e64 v71, v220, v71, s[14:15]
	v_max3_f32 v154, v154, v70, v71
	s_cmp_ge_i32 s4, 1
	s_cselect_b32 s6, s17, s71
	v_sub_f32_e32 v150, 0x43700000, v179
	v_sub_f32_e32 v151, 0x43710000, v179
	v_sub_f32_e32 v152, 0x43720000, v179
	v_sub_f32_e32 v153, 0x43730000, v179
	v_cmp_le_f32_e64 vcc, |v150|, s6
	v_fma_f32 v72, |v150|, -v147, v72
	v_cmp_le_f32_e64 s[14:15], |v151|, s6
	v_cndmask_b32_e32 v72, v220, v72, vcc
	v_fma_f32 v73, |v151|, -v147, v73
	v_cmp_le_f32_e64 vcc, |v152|, s6
	v_cndmask_b32_e64 v73, v220, v73, s[14:15]
; __device__ void attn_mfma(const Params& p, int l, const bf16_t* proj, bf16_t* y0, LAS unsigned char* lds) {
;     ...
;             for (int kt = 0; kt < 24; ++kt)
; #pragma unroll
;                 for (int r = 0; r < 4; ++r) { const float x = (float)(kt * 16 + r) - tq; float sc = fmaf(sacc[kt][r], 0.125f, -slope * fabsf(x));
;                     bool valid = fabsf(x) <= 128.0f;
;                     if (edge) { const int kl = kt * 16 + 4 * g + r; valid = valid && (n == 0 ? kl >= 128 : kl < 256); }
;                     sc = valid ? sc : -1e30f; sacc[kt][r] = sc; mx = fmaxf(mx, sc); }
;             mx = fmaxf(mx, __shfl_xor(mx, 16)); mx = fmaxf(mx, __shfl_xor(mx, 32));
;             float sum = 0.f; const float mxl = mx * 1.44269504f;
; #pragma unroll
;             for (int kt = 0; kt < 24; ++kt)
; #pragma unroll
;                 for (int r = 0; r < 4; ++r) { const float pr = exp2f(fmaf(sacc[kt][r], 1.44269504f, -mxl)); sacc[kt][r] = pr; sum += pr; }
;             sum += __shfl_xor(sum, 16); sum += __shfl_xor(sum, 32);
;             const float inv = 1.0f / (sum + __expf(sink - mx));
	v_fma_f32 v74, |v152|, -v147, v74
	v_cmp_le_f32_e64 s[14:15], |v153|, s6
	v_cndmask_b32_e32 v74, v220, v74, vcc
	v_fma_f32 v75, |v153|, -v147, v75
	v_max3_f32 v154, v154, v72, v73
	v_cndmask_b32_e64 v75, v220, v75, s[14:15]
	v_max3_f32 v154, v154, v74, v75
	s_cmp_ge_i32 s4, 0
	s_cselect_b32 s5, s17, s71
	v_sub_f32_e32 v150, 0x43800000, v179
	v_sub_f32_e32 v151, 0x43808000, v179
	v_sub_f32_e32 v152, 0x43810000, v179
	v_sub_f32_e32 v153, 0x43818000, v179
	v_cmp_le_f32_e64 vcc, |v150|, s5
	v_fma_f32 v76, |v150|, -v147, v76
	v_cmp_le_f32_e64 s[14:15], |v151|, s5
	v_cndmask_b32_e32 v76, v220, v76, vcc
	v_fma_f32 v77, |v151|, -v147, v77
	v_cmp_le_f32_e64 vcc, |v152|, s5
	v_cndmask_b32_e64 v77, v220, v77, s[14:15]
	v_fma_f32 v78, |v152|, -v147, v78
	v_cmp_le_f32_e64 s[14:15], |v153|, s5
	v_cndmask_b32_e32 v78, v220, v78, vcc
	v_fma_f32 v79, |v153|, -v147, v79
	v_max3_f32 v154, v154, v76, v77
	v_cndmask_b32_e64 v79, v220, v79, s[14:15]
	v_max3_f32 v154, v154, v78, v79
	v_mov_b32_e32 v155, v154
	s_nop 1
	v_permlane16_swap_b32_e32 v155, v154
	v_max_f32_e32 v154, v154, v155
	v_mov_b32_e32 v155, v154
	s_nop 1
	v_permlane32_swap_b32_e32 v155, v154
	v_max_f32_e32 v154, v154, v155
	v_mul_f32_e32 v156, 0xbe38aa3b, v154
	v_fmamk_f32 v158, v154, 0xbe000000, v146
	v_mul_f32_e32 v158, 0x3fb8aa3b, v158
	v_fmamk_f32 v12, v12, 0x3e38aa3b, v156
	v_fmamk_f32 v13, v13, 0x3e38aa3b, v156
	v_fmamk_f32 v14, v14, 0x3e38aa3b, v156
	v_fmamk_f32 v15, v15, 0x3e38aa3b, v156
	v_exp_f32_e32 v12, v12
	v_exp_f32_e32 v13, v13
	v_exp_f32_e32 v14, v14
	v_exp_f32_e32 v15, v15
	v_fmamk_f32 v16, v16, 0x3e38aa3b, v156
	v_fmamk_f32 v17, v17, 0x3e38aa3b, v156
	v_fmamk_f32 v18, v18, 0x3e38aa3b, v156
	v_fmamk_f32 v19, v19, 0x3e38aa3b, v156
	v_exp_f32_e32 v16, v16
	v_exp_f32_e32 v17, v17
	v_exp_f32_e32 v18, v18
	v_exp_f32_e32 v19, v19
	v_add_f32_e32 v157, v12, v13
	v_add_f32_e32 v157, v14, v157
	v_add_f32_e32 v157, v15, v157
	v_fmamk_f32 v20, v20, 0x3e38aa3b, v156
	v_fmamk_f32 v21, v21, 0x3e38aa3b, v156
	v_fmamk_f32 v22, v22, 0x3e38aa3b, v156
	v_fmamk_f32 v23, v23, 0x3e38aa3b, v156
	v_exp_f32_e32 v20, v20
	v_exp_f32_e32 v21, v21
	v_exp_f32_e32 v22, v22
	v_exp_f32_e32 v23, v23
	v_add_f32_e32 v157, v16, v157
	v_add_f32_e32 v157, v17, v157
	v_add_f32_e32 v157, v18, v157
	v_add_f32_e32 v157, v19, v157
	v_fmamk_f32 v24, v24, 0x3e38aa3b, v156
	v_fmamk_f32 v25, v25, 0x3e38aa3b, v156
	v_fmamk_f32 v26, v26, 0x3e38aa3b, v156
	v_fmamk_f32 v27, v27, 0x3e38aa3b, v156
	v_exp_f32_e32 v24, v24
	v_exp_f32_e32 v25, v25
	v_exp_f32_e32 v26, v26
	v_exp_f32_e32 v27, v27
	v_add_f32_e32 v157, v20, v157
	v_add_f32_e32 v157, v21, v157
	v_add_f32_e32 v157, v22, v157
	v_add_f32_e32 v157, v23, v157
	v_fmamk_f32 v28, v28, 0x3e38aa3b, v156
	v_fmamk_f32 v29, v29, 0x3e38aa3b, v156
	v_fmamk_f32 v30, v30, 0x3e38aa3b, v156
	v_fmamk_f32 v31, v31, 0x3e38aa3b, v156
	v_exp_f32_e32 v28, v28
	v_exp_f32_e32 v29, v29
	v_exp_f32_e32 v30, v30
	v_exp_f32_e32 v31, v31
	v_add_f32_e32 v157, v24, v157
	v_add_f32_e32 v157, v25, v157
	v_add_f32_e32 v157, v26, v157
	v_add_f32_e32 v157, v27, v157
	v_fmamk_f32 v32, v32, 0x3e38aa3b, v156
	v_fmamk_f32 v33, v33, 0x3e38aa3b, v156
	v_fmamk_f32 v34, v34, 0x3e38aa3b, v156
	v_fmamk_f32 v35, v35, 0x3e38aa3b, v156
	v_exp_f32_e32 v32, v32
	v_exp_f32_e32 v33, v33
	v_exp_f32_e32 v34, v34
	v_exp_f32_e32 v35, v35
	v_add_f32_e32 v157, v28, v157
	v_add_f32_e32 v157, v29, v157
	v_add_f32_e32 v157, v30, v157
	v_add_f32_e32 v157, v31, v157
	v_fmamk_f32 v36, v36, 0x3e38aa3b, v156
	v_fmamk_f32 v37, v37, 0x3e38aa3b, v156
	v_fmamk_f32 v38, v38, 0x3e38aa3b, v156
	v_fmamk_f32 v39, v39, 0x3e38aa3b, v156
	v_exp_f32_e32 v36, v36
	v_exp_f32_e32 v37, v37
	v_exp_f32_e32 v38, v38
	v_exp_f32_e32 v39, v39
	v_add_f32_e32 v157, v32, v157
	v_add_f32_e32 v157, v33, v157
	v_add_f32_e32 v157, v34, v157
	v_add_f32_e32 v157, v35, v157
	v_fmamk_f32 v40, v40, 0x3e38aa3b, v156
	v_fmamk_f32 v41, v41, 0x3e38aa3b, v156
	v_fmamk_f32 v42, v42, 0x3e38aa3b, v156
	v_fmamk_f32 v43, v43, 0x3e38aa3b, v156
	v_exp_f32_e32 v40, v40
	v_exp_f32_e32 v41, v41
	v_exp_f32_e32 v42, v42
	v_exp_f32_e32 v43, v43
	v_add_f32_e32 v157, v36, v157
	v_add_f32_e32 v157, v37, v157
	v_add_f32_e32 v157, v38, v157
	v_add_f32_e32 v157, v39, v157
	v_fmamk_f32 v44, v44, 0x3e38aa3b, v156
	v_fmamk_f32 v45, v45, 0x3e38aa3b, v156
	v_fmamk_f32 v46, v46, 0x3e38aa3b, v156
	v_fmamk_f32 v47, v47, 0x3e38aa3b, v156
	v_exp_f32_e32 v44, v44
	v_exp_f32_e32 v45, v45
	v_exp_f32_e32 v46, v46
	v_exp_f32_e32 v47, v47
	v_add_f32_e32 v157, v40, v157
	v_add_f32_e32 v157, v41, v157
	v_add_f32_e32 v157, v42, v157
	v_add_f32_e32 v157, v43, v157
	v_fmamk_f32 v48, v48, 0x3e38aa3b, v156
	v_fmamk_f32 v49, v49, 0x3e38aa3b, v156
	v_fmamk_f32 v50, v50, 0x3e38aa3b, v156
	v_fmamk_f32 v51, v51, 0x3e38aa3b, v156
	v_exp_f32_e32 v48, v48
	v_exp_f32_e32 v49, v49
	v_exp_f32_e32 v50, v50
	v_exp_f32_e32 v51, v51
	v_add_f32_e32 v157, v44, v157
	v_add_f32_e32 v157, v45, v157
	v_add_f32_e32 v157, v46, v157
	v_add_f32_e32 v157, v47, v157
	v_fmamk_f32 v52, v52, 0x3e38aa3b, v156
	v_fmamk_f32 v53, v53, 0x3e38aa3b, v156
	v_fmamk_f32 v54, v54, 0x3e38aa3b, v156
	v_fmamk_f32 v55, v55, 0x3e38aa3b, v156
	v_exp_f32_e32 v52, v52
	v_exp_f32_e32 v53, v53
	v_exp_f32_e32 v54, v54
	v_exp_f32_e32 v55, v55
	v_add_f32_e32 v157, v48, v157
	v_add_f32_e32 v157, v49, v157
	v_add_f32_e32 v157, v50, v157
	v_add_f32_e32 v157, v51, v157
	v_fmamk_f32 v56, v56, 0x3e38aa3b, v156
	v_fmamk_f32 v57, v57, 0x3e38aa3b, v156
	v_fmamk_f32 v58, v58, 0x3e38aa3b, v156
	v_fmamk_f32 v59, v59, 0x3e38aa3b, v156
	v_exp_f32_e32 v56, v56
	v_exp_f32_e32 v57, v57
	v_exp_f32_e32 v58, v58
	v_exp_f32_e32 v59, v59
	v_add_f32_e32 v157, v52, v157
	v_add_f32_e32 v157, v53, v157
; #define LAS __attribute__((address_space(3)))
; __device__ __forceinline__ unsigned cvt_pk_bf16_mfma(float lo, float hi) { const f32x2 v = {lo, hi}; return __builtin_bit_cast(unsigned, __builtin_convertvector(v, bf16v2_t)); }
; __device__ void attn_mfma(const Params& p, int l, const bf16_t* proj, bf16_t* y0, LAS unsigned char* lds) {
;     ...
;             float sum = 0.f; const float mxl = mx * 1.44269504f;
; #pragma unroll
;             for (int kt = 0; kt < 24; ++kt)
; #pragma unroll
;                 for (int r = 0; r < 4; ++r) { const float pr = exp2f(fmaf(sacc[kt][r], 1.44269504f, -mxl)); sacc[kt][r] = pr; sum += pr; }
;             sum += __shfl_xor(sum, 16); sum += __shfl_xor(sum, 32);
;             const float inv = 1.0f / (sum + __expf(sink - mx));
;             f32x4 oacc[4];
; #pragma unroll
;             for (int dt = 0; dt < 4; ++dt) oacc[dt] = (f32x4){0.f, 0.f, 0.f, 0.f};
; #pragma unroll
;             for (int i = 0; i < 12; ++i) {
;                 u32x4 pw; pw.x = cvt_pk_bf16_mfma(sacc[2 * i][0], sacc[2 * i][1]); pw.y = cvt_pk_bf16_mfma(sacc[2 * i][2], sacc[2 * i][3]); pw.z = cvt_pk_bf16_mfma(sacc[2 * i + 1][0], sacc[2 * i + 1][1]); pw.w = cvt_pk_bf16_mfma(sacc[2 * i + 1][2], sacc[2 * i + 1][3]);
;                 const bf16x8 pf = __builtin_bit_cast(bf16x8, pw);
; #pragma unroll
;                 for (int dt = 0; dt < 4; ++dt) { const LAS bf16_t* vp = Vt + (dt * 16 + fr) * VP + 32 * i + 4 * g;
;                     const u32x2 lo = *(const LAS u32x2*)vp, hi = *(const LAS u32x2*)(vp + 16);
;                     u32x4 vw; vw.x = lo.x; vw.y = lo.y; vw.z = hi.x; vw.w = hi.y;
;                     oacc[dt] = __builtin_amdgcn_mfma_f32_16x16x32_bf16(__builtin_bit_cast(bf16x8, vw), pf, oacc[dt], 0, 0, 0); }
;                 if (i & 1) __builtin_amdgcn_sched_barrier(0); }
	v_add_f32_e32 v157, v54, v157
	v_add_f32_e32 v157, v55, v157
	v_fmamk_f32 v60, v60, 0x3e38aa3b, v156
	v_fmamk_f32 v61, v61, 0x3e38aa3b, v156
	v_fmamk_f32 v62, v62, 0x3e38aa3b, v156
	v_fmamk_f32 v63, v63, 0x3e38aa3b, v156
	v_exp_f32_e32 v60, v60
	v_exp_f32_e32 v61, v61
	v_exp_f32_e32 v62, v62
	v_exp_f32_e32 v63, v63
	v_add_f32_e32 v157, v56, v157
	v_add_f32_e32 v157, v57, v157
	v_add_f32_e32 v157, v58, v157
	v_add_f32_e32 v157, v59, v157
	v_fmamk_f32 v64, v64, 0x3e38aa3b, v156
	v_fmamk_f32 v65, v65, 0x3e38aa3b, v156
	v_fmamk_f32 v66, v66, 0x3e38aa3b, v156
	v_fmamk_f32 v67, v67, 0x3e38aa3b, v156
	v_exp_f32_e32 v64, v64
	v_exp_f32_e32 v65, v65
	v_exp_f32_e32 v66, v66
	v_exp_f32_e32 v67, v67
	v_add_f32_e32 v157, v60, v157
	v_add_f32_e32 v157, v61, v157
	v_add_f32_e32 v157, v62, v157
	v_add_f32_e32 v157, v63, v157
	v_fmamk_f32 v68, v68, 0x3e38aa3b, v156
	v_fmamk_f32 v69, v69, 0x3e38aa3b, v156
	v_fmamk_f32 v70, v70, 0x3e38aa3b, v156
	v_fmamk_f32 v71, v71, 0x3e38aa3b, v156
	v_exp_f32_e32 v68, v68
	v_exp_f32_e32 v69, v69
	v_exp_f32_e32 v70, v70
	v_exp_f32_e32 v71, v71
	v_add_f32_e32 v157, v64, v157
	v_add_f32_e32 v157, v65, v157
	v_add_f32_e32 v157, v66, v157
	v_add_f32_e32 v157, v67, v157
	v_fmamk_f32 v72, v72, 0x3e38aa3b, v156
	v_fmamk_f32 v73, v73, 0x3e38aa3b, v156
	v_fmamk_f32 v74, v74, 0x3e38aa3b, v156
	v_fmamk_f32 v75, v75, 0x3e38aa3b, v156
	v_exp_f32_e32 v72, v72
	v_exp_f32_e32 v73, v73
	v_exp_f32_e32 v74, v74
	v_exp_f32_e32 v75, v75
	v_add_f32_e32 v157, v68, v157
	v_add_f32_e32 v157, v69, v157
	v_add_f32_e32 v157, v70, v157
	v_add_f32_e32 v157, v71, v157
	v_fmamk_f32 v76, v76, 0x3e38aa3b, v156
	v_fmamk_f32 v77, v77, 0x3e38aa3b, v156
	v_fmamk_f32 v78, v78, 0x3e38aa3b, v156
	v_fmamk_f32 v79, v79, 0x3e38aa3b, v156
	v_exp_f32_e32 v76, v76
	v_exp_f32_e32 v77, v77
	v_exp_f32_e32 v78, v78
	v_exp_f32_e32 v79, v79
	v_add_f32_e32 v157, v72, v157
	v_add_f32_e32 v157, v73, v157
	v_add_f32_e32 v157, v74, v157
	v_add_f32_e32 v157, v75, v157
	v_exp_f32_e32 v158, v158
	v_add_f32_e32 v157, v76, v157
	v_add_f32_e32 v157, v77, v157
	v_add_f32_e32 v157, v78, v157
	v_add_f32_e32 v157, v79, v157
	v_mov_b32_e32 v155, v157
	s_nop 1
	v_permlane16_swap_b32_e32 v155, v157
	v_add_f32_e32 v157, v157, v155
	v_mov_b32_e32 v155, v157
	s_nop 1
	v_permlane32_swap_b32_e32 v155, v157
	v_add_f32_e32 v157, v157, v155
	v_add_f32_e32 v159, v158, v157
	ds_read_b64 v[222:223], v181 offset:0
	ds_read_b64 v[224:225], v181 offset:32
	ds_read_b64 v[226:227], v182 offset:0
	ds_read_b64 v[228:229], v182 offset:32
	ds_read_b64 v[230:231], v183 offset:0
	ds_read_b64 v[232:233], v183 offset:32
	ds_read_b64 v[234:235], v184 offset:0
	ds_read_b64 v[236:237], v184 offset:32
	ds_read_b64 v[160:161], v181 offset:64
	ds_read_b64 v[162:163], v181 offset:96
	ds_read_b64 v[164:165], v182 offset:64
	ds_read_b64 v[166:167], v182 offset:96
	v_cvt_pk_bf16_f32 v12, v12, v13
	v_cvt_pk_bf16_f32 v13, v14, v15
	v_cvt_pk_bf16_f32 v14, v16, v17
	v_cvt_pk_bf16_f32 v15, v18, v19
	s_waitcnt lgkmcnt(8)
	ds_read_b64 v[96:97], v183 offset:64
	ds_read_b64 v[98:99], v183 offset:96
	ds_read_b64 v[104:105], v184 offset:64
	ds_read_b64 v[106:107], v184 offset:96
	v_cvt_pk_bf16_f32 v20, v20, v21
	v_cvt_pk_bf16_f32 v21, v22, v23
	v_cvt_pk_bf16_f32 v22, v24, v25
	v_cvt_pk_bf16_f32 v23, v26, v27
	v_mfma_f32_16x16x32_bf16 v[80:83], v[222:225], v[12:15], 0
	v_mfma_f32_16x16x32_bf16 v[84:87], v[226:229], v[12:15], 0
	s_waitcnt lgkmcnt(8)
	ds_read_b64 v[222:223], v181 offset:128
	ds_read_b64 v[224:225], v181 offset:160
	ds_read_b64 v[226:227], v182 offset:128
	ds_read_b64 v[228:229], v182 offset:160
	v_mfma_f32_16x16x32_bf16 v[88:91], v[230:233], v[12:15], 0
	v_mfma_f32_16x16x32_bf16 v[92:95], v[234:237], v[12:15], 0
	s_waitcnt lgkmcnt(8)
	ds_read_b64 v[230:231], v183 offset:128
	ds_read_b64 v[232:233], v183 offset:160
	ds_read_b64 v[234:235], v184 offset:128
	ds_read_b64 v[236:237], v184 offset:160
	v_cvt_pk_bf16_f32 v28, v28, v29
	v_cvt_pk_bf16_f32 v29, v30, v31
	v_cvt_pk_bf16_f32 v30, v32, v33
	v_cvt_pk_bf16_f32 v31, v34, v35
	v_mfma_f32_16x16x32_bf16 v[80:83], v[160:163], v[20:23], v[80:83]
	v_mfma_f32_16x16x32_bf16 v[84:87], v[164:167], v[20:23], v[84:87]
	s_waitcnt lgkmcnt(8)
	ds_read_b64 v[160:161], v181 offset:192
	ds_read_b64 v[162:163], v181 offset:224
	ds_read_b64 v[164:165], v182 offset:192
	ds_read_b64 v[166:167], v182 offset:224
	v_mfma_f32_16x16x32_bf16 v[88:91], v[96:99], v[20:23], v[88:91]
	v_mfma_f32_16x16x32_bf16 v[92:95], v[104:107], v[20:23], v[92:95]
	s_waitcnt lgkmcnt(8)
	ds_read_b64 v[96:97], v183 offset:192
	ds_read_b64 v[98:99], v183 offset:224
	ds_read_b64 v[104:105], v184 offset:192
	ds_read_b64 v[106:107], v184 offset:224
	v_cvt_pk_bf16_f32 v36, v36, v37
	v_cvt_pk_bf16_f32 v37, v38, v39
	v_cvt_pk_bf16_f32 v38, v40, v41
	v_cvt_pk_bf16_f32 v39, v42, v43
	v_mfma_f32_16x16x32_bf16 v[80:83], v[222:225], v[28:31], v[80:83]
	v_mfma_f32_16x16x32_bf16 v[84:87], v[226:229], v[28:31], v[84:87]
	s_waitcnt lgkmcnt(8)
	ds_read_b64 v[222:223], v181 offset:256
	ds_read_b64 v[224:225], v181 offset:288
	ds_read_b64 v[226:227], v182 offset:256
	ds_read_b64 v[228:229], v182 offset:288
	v_mfma_f32_16x16x32_bf16 v[88:91], v[230:233], v[28:31], v[88:91]
	v_mfma_f32_16x16x32_bf16 v[92:95], v[234:237], v[28:31], v[92:95]
	s_waitcnt lgkmcnt(8)
	ds_read_b64 v[230:231], v183 offset:256
	ds_read_b64 v[232:233], v183 offset:288
	ds_read_b64 v[234:235], v184 offset:256
	ds_read_b64 v[236:237], v184 offset:288
	v_cvt_pk_bf16_f32 v44, v44, v45
	v_cvt_pk_bf16_f32 v45, v46, v47
	v_cvt_pk_bf16_f32 v46, v48, v49
	v_cvt_pk_bf16_f32 v47, v50, v51
	v_mfma_f32_16x16x32_bf16 v[80:83], v[160:163], v[36:39], v[80:83]
	v_mfma_f32_16x16x32_bf16 v[84:87], v[164:167], v[36:39], v[84:87]
	s_waitcnt lgkmcnt(8)
; #define LAS __attribute__((address_space(3)))
; __device__ __forceinline__ unsigned cvt_pk_bf16(float lo, float hi) { unsigned r; asm("v_cvt_pk_bf16_f32 %0, %1, %2" : "=v"(r) : "v"(lo), "v"(hi)); return r; }
; __device__ __forceinline__ unsigned cvt_pk_bf16_mfma(float lo, float hi) { const f32x2 v = {lo, hi}; return __builtin_bit_cast(unsigned, __builtin_convertvector(v, bf16v2_t)); }
; __device__ void attn_mfma(const Params& p, int l, const bf16_t* proj, bf16_t* y0, LAS unsigned char* lds) {
;     ...
; #pragma unroll
;             for (int i = 0; i < 12; ++i) {
;                 u32x4 pw; pw.x = cvt_pk_bf16_mfma(sacc[2 * i][0], sacc[2 * i][1]); pw.y = cvt_pk_bf16_mfma(sacc[2 * i][2], sacc[2 * i][3]); pw.z = cvt_pk_bf16_mfma(sacc[2 * i + 1][0], sacc[2 * i + 1][1]); pw.w = cvt_pk_bf16_mfma(sacc[2 * i + 1][2], sacc[2 * i + 1][3]);
;                 const bf16x8 pf = __builtin_bit_cast(bf16x8, pw);
; #pragma unroll
;                 for (int dt = 0; dt < 4; ++dt) { const LAS bf16_t* vp = Vt + (dt * 16 + fr) * VP + 32 * i + 4 * g;
;                     const u32x2 lo = *(const LAS u32x2*)vp, hi = *(const LAS u32x2*)(vp + 16);
;                     u32x4 vw; vw.x = lo.x; vw.y = lo.y; vw.z = hi.x; vw.w = hi.y;
;                     oacc[dt] = __builtin_amdgcn_mfma_f32_16x16x32_bf16(__builtin_bit_cast(bf16x8, vw), pf, oacc[dt], 0, 0, 0); }
;                 if (i & 1) __builtin_amdgcn_sched_barrier(0); }
; #pragma unroll
;             for (int dt = 0; dt < 4; ++dt) { u32x2 w; w.x = cvt_pk_bf16(oacc[dt][0] * inv, oacc[dt][1] * inv); w.y = cvt_pk_bf16(oacc[dt][2] * inv, oacc[dt][3] * inv);
;                 *(u32x2*)(y0 + (size_t)t * 512 + hq * 64 + dt * 16 + 4 * g) = w; }
;         }
	ds_read_b64 v[160:161], v181 offset:320
	ds_read_b64 v[162:163], v181 offset:352
	ds_read_b64 v[164:165], v182 offset:320
	ds_read_b64 v[166:167], v182 offset:352
	v_mfma_f32_16x16x32_bf16 v[88:91], v[96:99], v[36:39], v[88:91]
	v_mfma_f32_16x16x32_bf16 v[92:95], v[104:107], v[36:39], v[92:95]
	s_waitcnt lgkmcnt(8)
	ds_read_b64 v[96:97], v183 offset:320
	ds_read_b64 v[98:99], v183 offset:352
	ds_read_b64 v[104:105], v184 offset:320
	ds_read_b64 v[106:107], v184 offset:352
	v_cvt_pk_bf16_f32 v52, v52, v53
	v_cvt_pk_bf16_f32 v53, v54, v55
	v_cvt_pk_bf16_f32 v54, v56, v57
	v_cvt_pk_bf16_f32 v55, v58, v59
	v_mfma_f32_16x16x32_bf16 v[80:83], v[222:225], v[44:47], v[80:83]
	v_mfma_f32_16x16x32_bf16 v[84:87], v[226:229], v[44:47], v[84:87]
	s_waitcnt lgkmcnt(8)
	ds_read_b64 v[222:223], v181 offset:384
	ds_read_b64 v[224:225], v181 offset:416
	ds_read_b64 v[226:227], v182 offset:384
	ds_read_b64 v[228:229], v182 offset:416
	v_mfma_f32_16x16x32_bf16 v[88:91], v[230:233], v[44:47], v[88:91]
	v_mfma_f32_16x16x32_bf16 v[92:95], v[234:237], v[44:47], v[92:95]
	s_waitcnt lgkmcnt(8)
	ds_read_b64 v[230:231], v183 offset:384
	ds_read_b64 v[232:233], v183 offset:416
	ds_read_b64 v[234:235], v184 offset:384
	ds_read_b64 v[236:237], v184 offset:416
	v_cvt_pk_bf16_f32 v60, v60, v61
	v_cvt_pk_bf16_f32 v61, v62, v63
	v_cvt_pk_bf16_f32 v62, v64, v65
	v_cvt_pk_bf16_f32 v63, v66, v67
	v_mfma_f32_16x16x32_bf16 v[80:83], v[160:163], v[52:55], v[80:83]
	v_mfma_f32_16x16x32_bf16 v[84:87], v[164:167], v[52:55], v[84:87]
	s_waitcnt lgkmcnt(8)
	ds_read_b64 v[160:161], v181 offset:448
	ds_read_b64 v[162:163], v181 offset:480
	ds_read_b64 v[164:165], v182 offset:448
	ds_read_b64 v[166:167], v182 offset:480
	v_mfma_f32_16x16x32_bf16 v[88:91], v[96:99], v[52:55], v[88:91]
	v_mfma_f32_16x16x32_bf16 v[92:95], v[104:107], v[52:55], v[92:95]
	s_waitcnt lgkmcnt(8)
	ds_read_b64 v[96:97], v183 offset:448
	ds_read_b64 v[98:99], v183 offset:480
	ds_read_b64 v[104:105], v184 offset:448
	ds_read_b64 v[106:107], v184 offset:480
	v_cvt_pk_bf16_f32 v68, v68, v69
	v_cvt_pk_bf16_f32 v69, v70, v71
	v_cvt_pk_bf16_f32 v70, v72, v73
	v_cvt_pk_bf16_f32 v71, v74, v75
	v_mfma_f32_16x16x32_bf16 v[80:83], v[222:225], v[60:63], v[80:83]
	v_mfma_f32_16x16x32_bf16 v[84:87], v[226:229], v[60:63], v[84:87]
	s_waitcnt lgkmcnt(8)
	ds_read_b64 v[222:223], v181 offset:512
	v_mov_b32_e32 v224, 0
	v_mov_b32_e32 v225, 0
	ds_read_b64 v[226:227], v182 offset:512
	v_mov_b32_e32 v228, 0
	v_mov_b32_e32 v229, 0
	v_mfma_f32_16x16x32_bf16 v[88:91], v[230:233], v[60:63], v[88:91]
	v_mfma_f32_16x16x32_bf16 v[92:95], v[234:237], v[60:63], v[92:95]
	s_waitcnt lgkmcnt(6)
	ds_read_b64 v[230:231], v183 offset:512
	v_mov_b32_e32 v232, 0
	v_mov_b32_e32 v233, 0
	ds_read_b64 v[234:235], v184 offset:512
	v_mov_b32_e32 v236, 0
	v_mov_b32_e32 v237, 0
	v_cvt_pk_bf16_f32 v76, v76, v77
	v_cvt_pk_bf16_f32 v77, v78, v79
	v_mov_b32_e32 v78, 0
	v_mov_b32_e32 v79, 0
	v_mfma_f32_16x16x32_bf16 v[80:83], v[160:163], v[68:71], v[80:83]
	v_mfma_f32_16x16x32_bf16 v[84:87], v[164:167], v[68:71], v[84:87]
	s_waitcnt lgkmcnt(4)
	v_mfma_f32_16x16x32_bf16 v[88:91], v[96:99], v[68:71], v[88:91]
	v_mfma_f32_16x16x32_bf16 v[92:95], v[104:107], v[68:71], v[92:95]
	s_waitcnt lgkmcnt(2)
	v_mfma_f32_16x16x32_bf16 v[80:83], v[222:225], v[76:79], v[80:83]
	v_mfma_f32_16x16x32_bf16 v[84:87], v[226:229], v[76:79], v[84:87]
	s_waitcnt lgkmcnt(0)
	v_mfma_f32_16x16x32_bf16 v[88:91], v[230:233], v[76:79], v[88:91]
	v_mfma_f32_16x16x32_bf16 v[92:95], v[234:237], v[76:79], v[92:95]
	v_div_scale_f32 v168, s[14:15], v159, v159, 1.0
	v_rcp_f32_e32 v169, v168
	v_div_scale_f32 v170, vcc, 1.0, v159, 1.0
	v_ashrrev_i32_e32 v119, 31, v118
	v_fma_f32 v171, -v168, v169, 1.0
	v_fmac_f32_e32 v169, v171, v169
	v_mul_f32_e32 v171, v170, v169
	v_fma_f32 v150, -v168, v171, v170
	v_fmac_f32_e32 v171, v150, v169
	v_fma_f32 v168, -v168, v171, v170
	v_div_fmas_f32 v168, v168, v169, v171
	v_div_fixup_f32 v170, v168, v159, 1.0
	v_lshlrev_b64 v[172:173], 10, v[118:119]
	v_lshl_add_u64 v[172:173], v[116:117], 0, v[172:173]
	s_nop 3
	v_mul_f32_e32 v80, v170, v80
	v_mul_f32_e32 v81, v170, v81
	v_mul_f32_e32 v82, v170, v82
	v_mul_f32_e32 v83, v170, v83
	v_mul_f32_e32 v84, v170, v84
	v_mul_f32_e32 v85, v170, v85
	v_mul_f32_e32 v86, v170, v86
	v_mul_f32_e32 v87, v170, v87
	v_mul_f32_e32 v88, v170, v88
	v_mul_f32_e32 v89, v170, v89
	v_mul_f32_e32 v90, v170, v90
	v_mul_f32_e32 v91, v170, v91
	v_mul_f32_e32 v92, v170, v92
	v_mul_f32_e32 v93, v170, v93
	v_mul_f32_e32 v94, v170, v94
	v_mul_f32_e32 v95, v170, v95
	v_cvt_pk_bf16_f32 v160, v80, v81
	v_cvt_pk_bf16_f32 v161, v82, v83
	v_cvt_pk_bf16_f32 v162, v84, v85
	v_cvt_pk_bf16_f32 v163, v86, v87
	v_cvt_pk_bf16_f32 v164, v88, v89
	v_cvt_pk_bf16_f32 v165, v90, v91
	v_cvt_pk_bf16_f32 v166, v92, v93
	v_cvt_pk_bf16_f32 v167, v94, v95
	s_waitcnt vmcnt(0)
	v_mov_b64_e32 v[100:101], v[0:1]
	v_mov_b64_e32 v[102:103], v[2:3]
	v_mov_b64_e32 v[8:9], v[4:5]
	v_mov_b64_e32 v[10:11], v[6:7]
	global_store_dwordx2 v[172:173], v[160:161], off
	global_store_dwordx2 v[172:173], v[162:163], off offset:32
	global_store_dwordx2 v[172:173], v[164:165], off offset:64
	global_store_dwordx2 v[172:173], v[166:167], off offset:96
	s_add_i32 s12, s12, 16
	s_cmp_eq_u32 s12, 64
	s_cbranch_scc0 .LBB0_478
	s_add_i32 s11, s11, s59
	s_cmpk_gt_i32 s11, 0xff
	s_cbranch_scc0 .LBB0_459
